# each workgroup loads an 8KiB slice of the kernel's own code at entry so later phases' instruction fetches hit L2; sample GLA gated-output loads batched
# speedup vs baseline: 1.0695x; 1.0222x over previous
; #define LAS __attribute__((address_space(3)))
; DI void p0_prep(const Params& p, LAS unsigned char* lds) {
;     int tid = threadIdx.x; asm volatile("" : "+v"(tid));
;     const int lane = tid & 63, wid = __builtin_amdgcn_readfirstlane(tid >> 6);
;     const int gw = blockIdx.x * 8 + wid, NGW = gridDim.x * 8;
;     unsigned char* ws = p.ws;
;     LAS float* scr = (LAS float*)(lds + wid * 8448);
;     constexpr int J1 = 28 * 128, J2 = J1 + 256, J3 = J2 + 256, J4 = J3 + 256, J5 = J4 + 128, J6 = J5 + 512;
;     for (int it = gw; it < J6; it += NGW) {
;         if (it < J1) {
;             int t = it >> 7; const int rem = it & 127, g = rem >> 4, kb = rem & 15; if (t >= 12) t += 1;
;             const bool sw = (t == 4 || t == 5 || t == 10 || t == 11);
;             const int src = (t < 12 ? 256 * t : 256 * (t - 1) + 16) + 32 * (sw ? g : lgrp(g));
;             transpose_item(p.w_in + (size_t)(64 * kb) * 7184 + src, 7184, (bf16_t*)(ws + OFF_WINT) + (size_t)(t * 256 + 32 * g) * 1024 + 64 * kb, 1024, scr, lane);
; __global__ void __launch_bounds__(512, 2) fwd_megakernel(Params p) {
;     extern __shared__ __attribute__((aligned(16))) unsigned char lds_raw[];
;     LAS unsigned char* lds = (LAS unsigned char*)lds_raw;
;     if (threadIdx.x < 4) ((volatile LAS unsigned*)(lds + LDS_BAR))[threadIdx.x] = 0u;
;     __syncthreads();
;     const XcdBarrier bar = xcd_barrier_post((unsigned*)(p.ws + OFF_BAR), (volatile LAS unsigned*)(lds + LDS_BAR));
;     if (p.ws == nullptr) cg::this_grid().sync();
;     p0_prep(p, lds);
.LBB0_18:
	s_or_b64 exec, exec, s[4:5]
	s_getpc_b64 s[100:101]
	s_lshr_b32 s4, s2, 3
	s_lshl_b32 s4, s4, 13
	v_lshlrev_b32_e32 v168, 4, v203
	v_add_u32_e32 v168, s4, v168
	v_cmp_gt_u32_e32 vcc, 0x25c00, v168
	s_and_saveexec_b64 s[4:5], vcc
	global_load_dwordx4 v[172:175], v168, s[100:101]
	s_or_b64 exec, exec, s[4:5]
	v_mov_b32_e32 v87, v203
	s_lshl_b32 s49, s2, 3
	v_readfirstlane_b32 s3, v87
	s_ashr_i32 s8, s3, 6
	s_load_dword s3, s[0:1], 0xd0
	s_add_i32 s20, s8, s49
	s_add_u32 s4, s0, 0xd0
	s_addc_u32 s5, s1, 0
	v_and_b32_e32 v1, 63, v87
	v_writelane_b32 v255, s4, 2
	s_waitcnt lgkmcnt(0)
	s_lshl_b32 s74, s3, 3
	s_cmpk_gt_i32 s20, 0x137f
	v_writelane_b32 v255, s5, 3
	v_lshlrev_b32_e32 v66, 3, v1
	s_cbranch_scc1 .LBB0_37
	s_mul_i32 s4, s8, 0x2100
	v_lshrrev_b32_e32 v75, 3, v1
	v_and_b32_e32 v0, 56, v66
	s_add_i32 s4, s4, 0
	v_lshrrev_b32_e32 v70, 5, v1
	v_and_b32_e32 v68, 31, v87
	v_mul_u32_u24_e32 v2, 0x84, v0
	v_lshlrev_b32_e32 v3, 2, v75
	v_or_b32_e32 v48, 24, v70
	v_add3_u32 v3, s4, v2, v3
	v_lshl_or_b32 v2, v70, 9, v68
	v_or_b32_e32 v60, 36, v70
	v_lshlrev_b32_e32 v5, 2, v2
	v_lshl_or_b32 v2, v48, 9, v68
	v_or_b32_e32 v72, 42, v70
	v_lshlrev_b32_e32 v29, 2, v2
	v_lshl_or_b32 v2, v60, 9, v68
	v_or_b32_e32 v74, 46, v70
	v_lshlrev_b32_e32 v41, 2, v2
	v_lshl_or_b32 v2, v72, 9, v68
	v_lshlrev_b32_e32 v47, 2, v2
	v_lshl_or_b32 v2, v74, 9, v68
	v_or_b32_e32 v76, 48, v70
	v_lshlrev_b32_e32 v51, 2, v2
	v_lshl_or_b32 v2, v76, 9, v68
	v_or_b32_e32 v77, 50, v70
	v_lshlrev_b32_e32 v53, 2, v2
	v_lshl_or_b32 v2, v77, 9, v68
	v_or_b32_e32 v78, 52, v70
	v_lshlrev_b32_e32 v55, 2, v2
	v_lshl_or_b32 v2, v78, 9, v68
	v_or_b32_e32 v79, 54, v70
	v_lshlrev_b32_e32 v57, 2, v2
	v_lshl_or_b32 v2, v79, 9, v68
	v_or_b32_e32 v80, 56, v70
	v_or_b32_e32 v26, 2, v70
	v_lshlrev_b32_e32 v59, 2, v2
	v_lshl_or_b32 v2, v80, 9, v68
	v_or_b32_e32 v81, 58, v70
	v_or_b32_e32 v50, 26, v70
	v_lshl_or_b32 v4, v26, 9, v68
	v_lshlrev_b32_e32 v61, 2, v2
	v_lshl_or_b32 v2, v81, 9, v68
	v_or_b32_e32 v82, 60, v70
	v_or_b32_e32 v62, 38, v70
	v_lshlrev_b32_e32 v7, 2, v4
	v_lshl_or_b32 v4, v50, 9, v68
	v_lshlrev_b32_e32 v63, 2, v2
	v_lshl_or_b32 v2, v82, 9, v68
	v_or_b32_e32 v83, 62, v70
	v_or_b32_e32 v73, 44, v70
	v_lshlrev_b32_e32 v31, 2, v4
	v_lshl_or_b32 v4, v62, 9, v68
	v_lshlrev_b32_e32 v67, 2, v2
	v_lshl_or_b32 v2, v83, 9, v68
	s_movk_i32 s5, 0x1c10
	v_lshlrev_b32_e32 v43, 2, v4
	v_lshl_or_b32 v4, v73, 9, v68
	v_lshlrev_b32_e32 v69, 2, v2
	v_mad_u32_u24 v2, v70, s5, v68
	v_lshlrev_b32_e32 v49, 2, v4
	v_add_u32_e32 v4, 0x3820, v2
	v_lshlrev_b32_e32 v89, 2, v4
	v_add_u32_e32 v4, 0x7040, v2
	v_lshlrev_b32_e32 v91, 2, v4
	v_add_u32_e32 v4, 0xa860, v2
	v_lshlrev_b32_e32 v93, 2, v4
	v_add_u32_e32 v4, 0xe080, v2
	v_lshlrev_b32_e32 v102, 2, v4
	v_add_u32_e32 v4, 0x118a0, v2
	v_lshlrev_b32_e32 v103, 2, v4
	v_add_u32_e32 v4, 0x150c0, v2
	v_lshlrev_b32_e32 v104, 2, v4
	v_add_u32_e32 v4, 0x188e0, v2
	v_lshlrev_b32_e32 v105, 2, v4
	v_add_u32_e32 v4, 0x1c100, v2
	v_lshlrev_b32_e32 v106, 2, v4
	v_add_u32_e32 v4, 0x1f920, v2
	v_lshlrev_b32_e32 v107, 2, v4
	v_add_u32_e32 v4, 0x23140, v2
	v_lshlrev_b32_e32 v108, 2, v4
	v_add_u32_e32 v4, 0x26960, v2
	v_lshlrev_b32_e32 v109, 2, v4
	v_add_u32_e32 v4, 0x2a180, v2
	v_lshlrev_b32_e32 v110, 2, v4
	v_add_u32_e32 v4, 0x2d9a0, v2
	v_lshlrev_b32_e32 v111, 2, v4
	v_add_u32_e32 v4, 0x311c0, v2
	v_lshlrev_b32_e32 v112, 2, v4
	v_add_u32_e32 v4, 0x349e0, v2
	v_lshlrev_b32_e32 v113, 2, v4
	v_add_u32_e32 v4, 0x38200, v2
	v_lshlrev_b32_e32 v114, 2, v4
	v_add_u32_e32 v4, 0x3ba20, v2
	v_lshlrev_b32_e32 v115, 2, v4
	v_add_u32_e32 v4, 0x3f240, v2
	v_lshlrev_b32_e32 v116, 2, v4
	v_add_u32_e32 v4, 0x42a60, v2
	v_lshlrev_b32_e32 v117, 2, v4
	v_add_u32_e32 v4, 0x46280, v2
	v_lshlrev_b32_e32 v118, 2, v4
	v_add_u32_e32 v4, 0x49aa0, v2
	v_lshlrev_b32_e32 v119, 2, v4
	v_add_u32_e32 v4, 0x4d2c0, v2
	v_lshlrev_b32_e32 v120, 2, v4
	v_add_u32_e32 v4, 0x50ae0, v2
	v_lshlrev_b32_e32 v121, 2, v4
	v_add_u32_e32 v4, 0x54300, v2
	v_lshlrev_b32_e32 v122, 2, v4
	v_add_u32_e32 v4, 0x57b20, v2
	v_lshlrev_b32_e32 v123, 2, v4
	v_add_u32_e32 v4, 0x5b340, v2
	v_lshlrev_b32_e32 v124, 2, v4
	v_add_u32_e32 v4, 0x5eb60, v2
	v_lshlrev_b32_e32 v125, 2, v4
	v_add_u32_e32 v4, 0x62380, v2
	v_lshlrev_b32_e32 v126, 2, v4
	v_add_u32_e32 v4, 0x65ba0, v2
	v_lshlrev_b32_e32 v127, 2, v4
	v_add_u32_e32 v4, 0x693c0, v2
	v_lshlrev_b32_e32 v129, 2, v2
; #define LAS __attribute__((address_space(3)))
; DI unsigned pk2(float a, float b) { f32x2 v = {a, b}; bf2v r = __builtin_convertvector(v, bf2v); return __builtin_bit_cast(unsigned, r); }
; #define LDS_WAIT() asm volatile("s_waitcnt lgkmcnt(0)" ::: "memory")
; DI void transpose_item(const float* W, int ldw, bf16_t* WT, int ldt, LAS float* scr, int lane) {
;     float tv[32];
; #pragma unroll
;     for (int i = 0; i < 32; ++i) tv[i] = W[(size_t)(2 * i + (lane >> 5)) * ldw + (lane & 31)];
; #pragma unroll
;     for (int i = 0; i < 32; ++i) scr[(2 * i + (lane >> 5)) * 33 + (lane & 31)] = tv[i];
;     LDS_WAIT();
;     const int c = lane & 7;
; #pragma unroll
;     for (int j = 0; j < 4; ++j) {
;         const int n = (lane >> 3) + 8 * j; const LAS float* s = scr + (8 * c) * 33 + n;
;         u32x4 o; o.x = pk2(s[0 * 33], s[1 * 33]); o.y = pk2(s[2 * 33], s[3 * 33]); o.z = pk2(s[4 * 33], s[5 * 33]); o.w = pk2(s[6 * 33], s[7 * 33]);
;         *(u32x4*)(WT + (size_t)n * ldt + 8 * c) = o;
; DI void p0_prep(const Params& p, LAS unsigned char* lds) {
;     ...
;     LAS float* scr = (LAS float*)(lds + wid * 8448);
;     constexpr int J1 = 28 * 128, J2 = J1 + 256, J3 = J2 + 256, J4 = J3 + 256, J5 = J4 + 128, J6 = J5 + 512;
;     for (int it = gw; it < J6; it += NGW) {
;         if (it < J1) {
;             int t = it >> 7; const int rem = it & 127, g = rem >> 4, kb = rem & 15; if (t >= 12) t += 1;
;             const bool sw = (t == 4 || t == 5 || t == 10 || t == 11);
;             const int src = (t < 12 ? 256 * t : 256 * (t - 1) + 16) + 32 * (sw ? g : lgrp(g));
;             transpose_item(p.w_in + (size_t)(64 * kb) * 7184 + src, 7184, (bf16_t*)(ws + OFF_WINT) + (size_t)(t * 256 + 32 * g) * 1024 + 64 * kb, 1024, scr, lane);
	v_add_u32_e32 v2, 0x6cbe0, v2
	v_lshlrev_b32_e32 v130, 2, v2
	s_movk_i32 s5, 0x84
	v_mov_b32_e32 v2, 0x630
	v_mad_u32_u24 v131, v70, s5, v2
	v_mov_b32_e32 v2, 0xc60
	v_mad_u32_u24 v132, v70, s5, v2
	v_mov_b32_e32 v2, 0x1290
	v_mad_u32_u24 v133, v70, s5, v2
	v_mov_b32_e32 v2, 0x18c0
	v_or_b32_e32 v28, 4, v70
	v_mad_u32_u24 v134, v70, s5, v2
	v_lshl_add_u32 v135, v68, 2, s4
	s_load_dwordx4 s[4:7], s[0:1], 0xb0
	s_load_dwordx2 s[10:11], s[0:1], 0x88
	s_load_dwordx2 s[12:13], s[0:1], 0x48
	v_or_b32_e32 v30, 6, v70
	v_or_b32_e32 v32, 8, v70
	v_or_b32_e32 v34, 10, v70
	v_or_b32_e32 v38, 14, v70
	v_or_b32_e32 v42, 18, v70
	v_or_b32_e32 v52, 28, v70
	v_lshl_or_b32 v6, v28, 9, v68
	v_or_b32_e32 v36, 12, v70
	v_or_b32_e32 v40, 16, v70
	v_or_b32_e32 v44, 20, v70
	v_or_b32_e32 v46, 22, v70
	v_or_b32_e32 v54, 30, v70
	v_or_b32_e32 v56, 32, v70
	v_or_b32_e32 v58, 34, v70
	v_or_b32_e32 v71, 40, v70
	v_lshl_or_b32 v8, v30, 9, v68
	v_lshl_or_b32 v10, v32, 9, v68
	v_lshl_or_b32 v12, v34, 9, v68
	v_lshl_or_b32 v16, v38, 9, v68
	v_lshl_or_b32 v20, v42, 9, v68
	v_lshlrev_b32_e32 v9, 2, v6
	v_lshl_or_b32 v6, v52, 9, v68
	v_lshl_or_b32 v14, v36, 9, v68
	v_lshl_or_b32 v18, v40, 9, v68
	v_lshl_or_b32 v22, v44, 9, v68
	v_lshl_or_b32 v24, v46, 9, v68
	v_lshlrev_b32_e32 v11, 2, v8
	v_lshlrev_b32_e32 v13, 2, v10
	v_lshlrev_b32_e32 v15, 2, v12
	v_lshl_or_b32 v8, v54, 9, v68
	v_lshlrev_b32_e32 v19, 2, v16
	v_lshl_or_b32 v10, v56, 9, v68
	v_lshlrev_b32_e32 v23, 2, v20
	v_lshl_or_b32 v12, v58, 9, v68
	v_lshlrev_b32_e32 v33, 2, v6
	v_lshl_or_b32 v6, v71, 9, v68
	v_lshl_or_b32 v2, v26, 10, v68
	v_lshl_or_b32 v16, v40, 10, v68
	v_lshl_or_b32 v20, v44, 10, v68
	v_lshl_or_b32 v26, v50, 10, v68
	v_lshl_or_b32 v40, v71, 10, v68
	v_lshl_or_b32 v44, v73, 10, v68
	v_lshl_or_b32 v50, v77, 10, v68
	v_or_b32_e32 v71, 8, v75
	v_or_b32_e32 v73, 16, v75
	v_or_b32_e32 v77, 24, v75
	v_lshlrev_b32_e32 v17, 2, v14
	v_lshlrev_b32_e32 v21, 2, v18
	v_lshlrev_b32_e32 v25, 2, v22
	v_lshlrev_b32_e32 v27, 2, v24
	v_lshlrev_b32_e32 v35, 2, v8
	v_lshlrev_b32_e32 v37, 2, v10
	v_lshlrev_b32_e32 v39, 2, v12
	v_lshlrev_b32_e32 v45, 2, v6
	v_lshlrev_b32_e32 v128, 2, v4
	s_mov_b64 s[14:15], 0x1100000
	v_lshl_or_b32 v4, v28, 10, v68
	v_lshl_or_b32 v6, v30, 10, v68
	v_lshl_or_b32 v8, v32, 10, v68
	v_lshl_or_b32 v10, v34, 10, v68
	v_lshl_or_b32 v12, v36, 10, v68
	v_lshl_or_b32 v14, v38, 10, v68
	v_lshl_or_b32 v18, v42, 10, v68
	v_lshl_or_b32 v22, v46, 10, v68
	v_lshl_or_b32 v24, v48, 10, v68
	v_lshl_or_b32 v28, v52, 10, v68
	v_lshl_or_b32 v30, v54, 10, v68
	v_lshl_or_b32 v32, v56, 10, v68
	v_lshl_or_b32 v34, v58, 10, v68
	v_lshl_or_b32 v36, v60, 10, v68
	v_lshl_or_b32 v38, v62, 10, v68
	v_lshl_or_b32 v42, v72, 10, v68
	v_lshl_or_b32 v46, v74, 10, v68
	v_lshl_or_b32 v48, v76, 10, v68
	v_lshl_or_b32 v52, v78, 10, v68
	v_lshl_or_b32 v54, v79, 10, v68
	v_lshl_or_b32 v56, v80, 10, v68
	v_lshl_or_b32 v58, v81, 10, v68
	v_lshl_or_b32 v60, v82, 10, v68
	v_lshl_or_b32 v62, v83, 10, v68
	v_lshl_or_b32 v68, v70, 10, v68
	v_mul_u32_u24_e32 v136, 0x84, v70
	s_mov_b64 s[28:29], 0x1080000
	s_mov_b64 s[30:31], 0x1300000
	s_lshl_b32 s16, s2, 4
	s_lshl_b32 s17, s8, 1
	s_lshl_b32 s18, s2, 6
	s_lshl_b32 s19, s8, 3
	s_lshl_b32 s21, s2, 9
	s_lshl_b32 s22, s8, 6
	s_lshl_b32 s23, s2, 5
	s_lshl_b32 s8, s8, 2
	v_lshlrev_b32_e32 v70, 8, v75
	v_lshlrev_b32_e32 v72, 8, v71
	v_lshlrev_b32_e32 v74, 8, v73
	v_lshlrev_b32_e32 v76, 8, v77
	v_lshlrev_b32_e32 v78, 9, v75
	v_lshlrev_b32_e32 v80, 9, v71
	v_lshlrev_b32_e32 v82, 9, v73
	v_lshlrev_b32_e32 v84, 9, v77
	s_mov_b32 s9, 0
	s_add_i32 s16, s16, s17
	s_lshl_b32 s17, s3, 4
	s_add_i32 s18, s18, s19
	s_lshl_b32 s19, s3, 6
	s_add_i32 s21, s21, s22
	s_lshl_b32 s22, s3, 9
	s_add_i32 s23, s23, s8
	s_lshl_b32 s24, s3, 5
	v_lshlrev_b32_e32 v70, 1, v70
	v_lshlrev_b32_e32 v72, 1, v72
	v_lshlrev_b32_e32 v74, 1, v74
	v_lshlrev_b32_e32 v76, 1, v76
	s_mov_b32 s25, 0xe80000
	s_movk_i32 s26, 0xa0
	v_lshlrev_b32_e32 v78, 1, v78
	v_lshlrev_b32_e32 v80, 1, v80
	v_lshlrev_b32_e32 v82, 1, v82
	v_lshlrev_b32_e32 v84, 1, v84
	s_mov_b32 s27, s20
	v_lshlrev_b32_e32 v86, 10, v75
	v_lshlrev_b32_e32 v88, 10, v71
	v_lshlrev_b32_e32 v90, 10, v73
	v_lshlrev_b32_e32 v92, 10, v77
	v_lshl_add_u64 v[94:95], v[64:65], 0, s[14:15]
	v_mov_b32_e32 v97, 0
	v_lshl_add_u64 v[98:99], v[64:65], 0, s[28:29]
	v_lshl_add_u64 v[100:101], v[64:65], 0, s[30:31]
	s_branch .LBB0_21

; #define LAS __attribute__((address_space(3)))
; DI bf16_t f2bf(float a) { return (bf16_t)(pk2(a, 0.f) & 0xffffu); }
; DI float bf2f(bf16_t v) { return __uint_as_float(((unsigned)v) << 16); }
; template <bool SAMPLE>
; DI void gla_out(const Params& p, int item, int tbsel, LAS unsigned char* wl, int lane) {
;     ...
;     if (SAMPLE) { sb = item >> 2; h = item & 3; t0 = T_P + 16 * sb; }
;     else { c = item & 127; const int bh = item >> 7; h = bh & 3; b = bh >> 2; t0 = b * 8192 + 64 * c; }
;     const float* la = (const float*)(ws + OFF_LOGA) + (size_t)t0 * 256 + h * 64 + lane;
;     const bf16_t* qb = (const bf16_t*)(ws + OFF_QB) + (size_t)t0 * 256 + h * 64 + lane;
;     const bf16_t* kb = (const bf16_t*)(ws + OFF_KB) + (size_t)t0 * 256 + h * 64 + lane;
;     LAS unsigned char* Qs = wl; LAS unsigned char* Ks = wl + 9216;
;     float cum = 0.f;
;     constexpr int HB = SAMPLE ? 16 : 32;
;     const int tb = SAMPLE ? 0 : tbsel;
;     const int nhalf = SAMPLE ? 1 : tb + 1;
; #pragma unroll 1
;     for (int hf = 0; hf < nhalf; ++hf) {
;         float lav[HB]; bf16_t qvv[HB], kvv[HB];
; #pragma unroll
;         for (int t = 0; t < HB; ++t) { lav[t] = la[(hf * 32 + t) * 256]; qvv[t] = qb[(hf * 32 + t) * 256]; kvv[t] = kb[(hf * 32 + t) * 256]; }
; #pragma unroll
;         for (int t = 0; t < HB; ++t) {
;             cum += lav[t];
;             const float qv = bf2f(qvv[t]) * __expf(cum), kv = bf2f(kvv[t]) * __expf(-cum);
;             *(LAS bf16_t*)(Qs + (hf * 32 + t) * 144 + 2 * lane) = f2bf(qv);
;             *(LAS bf16_t*)(Ks + (hf * 32 + t) * 144 + 2 * lane) = f2bf(kv);
;         }
.LBB0_1009:
	s_ashr_i32 s38, s28, 2
	s_lshl_b32 s22, s38, 4
	s_add_i32 s72, s22, 0x4000
	s_ashr_i32 s73, s72, 31
	s_lshl_b64 s[22:23], s[72:73], 10
	v_lshl_add_u64 v[180:181], v[146:147], 0, s[22:23]
	s_lshl_b64 s[22:23], s[72:73], 9
	v_lshl_add_u64 v[0:1], v[174:175], 0, s[22:23]
	v_lshl_add_u64 v[182:183], v[176:177], 0, s[22:23]
	global_load_dword v10, v[180:181], off
	global_load_ushort v11, v[0:1], off
	global_load_ushort v12, v[182:183], off
	global_load_dword v13, v[180:181], off offset:1024
	global_load_ushort v14, v[0:1], off offset:512
	global_load_dword v15, v[180:181], off offset:2048
	global_load_dword v16, v[180:181], off offset:3072
	global_load_ushort v17, v[182:183], off offset:512
	global_load_ushort v18, v[182:183], off offset:1024
	global_load_ushort v19, v[182:183], off offset:1536
	global_load_ushort v20, v[0:1], off offset:1024
	global_load_ushort v21, v[0:1], off offset:1536
	global_load_ushort v22, v[182:183], off offset:2048
	global_load_ushort v23, v[182:183], off offset:2560
	global_load_ushort v24, v[182:183], off offset:3072
	global_load_ushort v25, v[182:183], off offset:3584
	v_add_co_u32_e64 v4, s[22:23], s49, v0
	v_add_co_u32_e32 v2, vcc, 0x1000, v180
	s_nop 0
	v_addc_co_u32_e64 v5, s[22:23], 0, v1, s[22:23]
	v_add_co_u32_e64 v6, s[22:23], s49, v182
	v_addc_co_u32_e32 v3, vcc, 0, v181, vcc
	s_nop 0
	v_addc_co_u32_e64 v7, s[22:23], 0, v183, s[22:23]
	global_load_ushort v26, v[4:5], off
	global_load_ushort v27, v[4:5], off offset:512
	global_load_ushort v28, v[4:5], off offset:1024
	global_load_ushort v29, v[4:5], off offset:1536
	global_load_ushort v30, v[4:5], off offset:2048
	global_load_ushort v31, v[4:5], off offset:2560
	global_load_ushort v32, v[4:5], off offset:3072
	global_load_ushort v33, v[4:5], off offset:3584
	global_load_ushort v34, v[0:1], off offset:2048
	global_load_dword v35, v[2:3], off
	global_load_ushort v36, v[6:7], off
	global_load_ushort v37, v[6:7], off offset:512
	global_load_ushort v38, v[6:7], off offset:1024
	global_load_ushort v39, v[6:7], off offset:1536
	global_load_ushort v40, v[6:7], off offset:2048
	global_load_ushort v41, v[6:7], off offset:2560
	global_load_ushort v42, v[6:7], off offset:3072
	s_nop 0
	global_load_ushort v6, v[6:7], off offset:3584
	s_nop 0
	global_load_ushort v7, v[0:1], off offset:2560
	global_load_ushort v43, v[0:1], off offset:3072
	global_load_dword v44, v[2:3], off offset:1024
	global_load_dword v45, v[2:3], off offset:2048
	s_nop 0
	global_load_dword v2, v[2:3], off offset:3072
	s_nop 0
	global_load_ushort v0, v[0:1], off offset:3584
	v_add_co_u32_e32 v8, vcc, 0x2000, v180
	s_ashr_i32 s29, s28, 31
	s_nop 0
	v_addc_co_u32_e32 v9, vcc, 0, v181, vcc
	v_add_co_u32_e32 v4, vcc, 0x3000, v180
	s_lshl_b64 s[22:23], s[28:29], 15
	s_nop 0
	v_addc_co_u32_e32 v5, vcc, 0, v181, vcc
	global_load_dword v1, v[8:9], off
	global_load_dword v3, v[8:9], off offset:1024
	global_load_dword v46, v[8:9], off offset:2048
	s_nop 0
	global_load_dword v8, v[8:9], off offset:3072
	s_nop 0
	global_load_dword v9, v[4:5], off
	global_load_dword v47, v[4:5], off offset:1024
	global_load_dword v48, v[4:5], off offset:2048
	s_nop 0
	global_load_dword v4, v[4:5], off offset:3072
	v_add_u32_e32 v202, v184, v145
	v_cmp_lt_i32_e32 vcc, v188, v189
	s_waitcnt vmcnt(47)
	v_add_f32_e32 v5, 0, v10
	s_waitcnt vmcnt(46)
	v_lshlrev_b32_e32 v10, 16, v11
	s_waitcnt vmcnt(45)
	v_lshlrev_b32_e32 v11, 16, v12
	v_mul_f32_e32 v12, 0x3fb8aa3b, v5
	v_mul_f32_e32 v49, 0xbfb8aa3b, v5
	v_exp_f32_e32 v12, v12
	v_exp_f32_e32 v49, v49
	s_waitcnt vmcnt(44)
	v_add_f32_e32 v5, v5, v13
	v_mul_f32_e32 v13, 0x3fb8aa3b, v5
	v_mul_f32_e32 v10, v12, v10
	v_mul_f32_e32 v11, v49, v11
	v_cvt_pk_bf16_f32 v10, v10, s0
	v_cvt_pk_bf16_f32 v11, v11, s0
	ds_write_b16 v190, v10 offset:8448
	ds_write_b16 v190, v11 offset:17664
	v_exp_f32_e32 v10, v13
	v_mul_f32_e32 v11, 0xbfb8aa3b, v5
	v_exp_f32_e32 v11, v11
	s_waitcnt vmcnt(43)
	v_lshlrev_b32_e32 v12, 16, v14
	v_mul_f32_e32 v10, v10, v12
	s_waitcnt vmcnt(40)
	v_lshlrev_b32_e32 v12, 16, v17
	v_mul_f32_e32 v11, v11, v12
	v_cvt_pk_bf16_f32 v10, v10, s0
	ds_write_b16 v190, v10 offset:8592
	v_cvt_pk_bf16_f32 v10, v11, s0
	v_add_f32_e32 v5, v5, v15
	ds_write_b16 v190, v10 offset:17808
	v_mul_f32_e32 v10, 0x3fb8aa3b, v5
	v_exp_f32_e32 v10, v10
	v_mul_f32_e32 v11, 0xbfb8aa3b, v5
	v_exp_f32_e32 v11, v11
	s_waitcnt vmcnt(37)
	v_lshlrev_b32_e32 v12, 16, v20
	v_mul_f32_e32 v10, v10, v12
	v_lshlrev_b32_e32 v12, 16, v18
	v_mul_f32_e32 v11, v11, v12
	v_cvt_pk_bf16_f32 v10, v10, s0
	ds_write_b16 v190, v10 offset:8736
	v_cvt_pk_bf16_f32 v10, v11, s0
	v_add_f32_e32 v5, v5, v16
	ds_write_b16 v190, v10 offset:17952
	v_mul_f32_e32 v10, 0x3fb8aa3b, v5
	v_exp_f32_e32 v10, v10
	v_mul_f32_e32 v11, 0xbfb8aa3b, v5
	v_exp_f32_e32 v11, v11
	s_waitcnt vmcnt(36)
	v_lshlrev_b32_e32 v12, 16, v21
	v_mul_f32_e32 v10, v10, v12
	v_lshlrev_b32_e32 v12, 16, v19
	v_mul_f32_e32 v11, v11, v12
	v_cvt_pk_bf16_f32 v10, v10, s0
	ds_write_b16 v190, v10 offset:8880
	v_cvt_pk_bf16_f32 v10, v11, s0
	s_waitcnt vmcnt(22)
	v_add_f32_e32 v5, v5, v35
	ds_write_b16 v190, v10 offset:18096
	v_mul_f32_e32 v10, 0x3fb8aa3b, v5
	v_exp_f32_e32 v10, v10
	v_mul_f32_e32 v11, 0xbfb8aa3b, v5
	v_exp_f32_e32 v11, v11
	v_lshlrev_b32_e32 v12, 16, v34
	v_mul_f32_e32 v10, v10, v12
	v_lshlrev_b32_e32 v12, 16, v22
	v_mul_f32_e32 v11, v11, v12
	v_cvt_pk_bf16_f32 v10, v10, s0
	ds_write_b16 v190, v10 offset:9024
	v_cvt_pk_bf16_f32 v10, v11, s0
	s_waitcnt vmcnt(11)
; #define LAS __attribute__((address_space(3)))
; DI bf16_t f2bf(float a) { return (bf16_t)(pk2(a, 0.f) & 0xffffu); }
; DI float bf2f(bf16_t v) { return __uint_as_float(((unsigned)v) << 16); }
; template <bool SAMPLE>
; DI void gla_out(const Params& p, int item, int tbsel, LAS unsigned char* wl, int lane) {
;     ...
; #pragma unroll
;         for (int t = 0; t < HB; ++t) {
;             cum += lav[t];
;             const float qv = bf2f(qvv[t]) * __expf(cum), kv = bf2f(kvv[t]) * __expf(-cum);
;             *(LAS bf16_t*)(Qs + (hf * 32 + t) * 144 + 2 * lane) = f2bf(qv);
;             *(LAS bf16_t*)(Ks + (hf * 32 + t) * 144 + 2 * lane) = f2bf(kv);
;         }
;     }
;     if (SAMPLE) {
; #pragma unroll
;         for (int t = 16; t < 32; ++t) { *(LAS bf16_t*)(Qs + t * 144 + 2 * lane) = 0; *(LAS bf16_t*)(Ks + t * 144 + 2 * lane) = 0; }
;     }
	v_add_f32_e32 v5, v5, v44
	ds_write_b16 v190, v10 offset:18240
	v_mul_f32_e32 v10, 0x3fb8aa3b, v5
	v_exp_f32_e32 v10, v10
	v_mul_f32_e32 v11, 0xbfb8aa3b, v5
	v_exp_f32_e32 v11, v11
	v_lshlrev_b32_e32 v7, 16, v7
	v_mul_f32_e32 v7, v10, v7
	v_lshlrev_b32_e32 v10, 16, v23
	v_mul_f32_e32 v10, v11, v10
	v_cvt_pk_bf16_f32 v7, v7, s0
	ds_write_b16 v190, v7 offset:9168
	v_cvt_pk_bf16_f32 v7, v10, s0
	s_waitcnt vmcnt(10)
	v_add_f32_e32 v5, v5, v45
	ds_write_b16 v190, v7 offset:18384
	v_mul_f32_e32 v7, 0x3fb8aa3b, v5
	v_exp_f32_e32 v7, v7
	v_mul_f32_e32 v10, 0xbfb8aa3b, v5
	v_exp_f32_e32 v10, v10
	v_lshlrev_b32_e32 v11, 16, v43
	v_mul_f32_e32 v7, v7, v11
	v_lshlrev_b32_e32 v11, 16, v24
	v_mul_f32_e32 v10, v10, v11
	v_cvt_pk_bf16_f32 v7, v7, s0
	s_waitcnt vmcnt(9)
	v_add_f32_e32 v2, v5, v2
	ds_write_b16 v190, v7 offset:9312
	v_cvt_pk_bf16_f32 v7, v10, s0
	v_mul_f32_e32 v5, 0x3fb8aa3b, v2
	ds_write_b16 v190, v7 offset:18528
	v_exp_f32_e32 v5, v5
	v_mul_f32_e32 v7, 0xbfb8aa3b, v2
	v_exp_f32_e32 v7, v7
	s_waitcnt vmcnt(8)
	v_lshlrev_b32_e32 v0, 16, v0
	v_mul_f32_e32 v0, v5, v0
	v_lshlrev_b32_e32 v5, 16, v25
	v_mul_f32_e32 v5, v7, v5
	v_cvt_pk_bf16_f32 v0, v0, s0
	ds_write_b16 v190, v0 offset:9456
	v_cvt_pk_bf16_f32 v0, v5, s0
	ds_write_b16 v190, v0 offset:18672
	s_waitcnt vmcnt(7)
	v_add_f32_e32 v0, v2, v1
	v_mul_f32_e32 v1, 0x3fb8aa3b, v0
	v_exp_f32_e32 v1, v1
	v_mul_f32_e32 v2, 0xbfb8aa3b, v0
	v_exp_f32_e32 v2, v2
	v_lshlrev_b32_e32 v5, 16, v26
	v_mul_f32_e32 v1, v1, v5
	v_lshlrev_b32_e32 v5, 16, v36
	v_mul_f32_e32 v2, v2, v5
	v_cvt_pk_bf16_f32 v1, v1, s0
	ds_write_b16 v190, v1 offset:9600
	v_cvt_pk_bf16_f32 v1, v2, s0
	s_waitcnt vmcnt(6)
	v_add_f32_e32 v0, v0, v3
	ds_write_b16 v190, v1 offset:18816
	v_mul_f32_e32 v1, 0x3fb8aa3b, v0
	v_exp_f32_e32 v1, v1
	v_mul_f32_e32 v2, 0xbfb8aa3b, v0
	v_exp_f32_e32 v2, v2
	v_lshlrev_b32_e32 v3, 16, v27
	v_mul_f32_e32 v1, v1, v3
	v_lshlrev_b32_e32 v3, 16, v37
	v_mul_f32_e32 v2, v2, v3
	v_cvt_pk_bf16_f32 v1, v1, s0
	ds_write_b16 v190, v1 offset:9744
	v_cvt_pk_bf16_f32 v1, v2, s0
	s_waitcnt vmcnt(5)
	v_add_f32_e32 v0, v0, v46
	ds_write_b16 v190, v1 offset:18960
	v_mul_f32_e32 v1, 0x3fb8aa3b, v0
	v_exp_f32_e32 v1, v1
	v_mul_f32_e32 v2, 0xbfb8aa3b, v0
	v_exp_f32_e32 v2, v2
	v_lshlrev_b32_e32 v3, 16, v28
	v_mul_f32_e32 v1, v1, v3
	v_lshlrev_b32_e32 v3, 16, v38
	v_mul_f32_e32 v2, v2, v3
	v_cvt_pk_bf16_f32 v1, v1, s0
	ds_write_b16 v190, v1 offset:9888
	v_cvt_pk_bf16_f32 v1, v2, s0
	s_waitcnt vmcnt(4)
	v_add_f32_e32 v0, v0, v8
	ds_write_b16 v190, v1 offset:19104
	v_mul_f32_e32 v1, 0x3fb8aa3b, v0
	v_exp_f32_e32 v1, v1
	v_mul_f32_e32 v2, 0xbfb8aa3b, v0
	v_exp_f32_e32 v2, v2
	v_lshlrev_b32_e32 v3, 16, v29
	v_mul_f32_e32 v1, v1, v3
	v_lshlrev_b32_e32 v3, 16, v39
	v_mul_f32_e32 v2, v2, v3
	v_cvt_pk_bf16_f32 v1, v1, s0
	ds_write_b16 v190, v1 offset:10032
	v_cvt_pk_bf16_f32 v1, v2, s0
	s_waitcnt vmcnt(3)
	v_add_f32_e32 v0, v0, v9
	ds_write_b16 v190, v1 offset:19248
	v_mul_f32_e32 v1, 0x3fb8aa3b, v0
	v_exp_f32_e32 v1, v1
	v_mul_f32_e32 v2, 0xbfb8aa3b, v0
	v_exp_f32_e32 v2, v2
	v_lshlrev_b32_e32 v3, 16, v30
	v_mul_f32_e32 v1, v1, v3
	v_lshlrev_b32_e32 v3, 16, v40
	v_mul_f32_e32 v2, v2, v3
	v_cvt_pk_bf16_f32 v1, v1, s0
	ds_write_b16 v190, v1 offset:10176
	v_cvt_pk_bf16_f32 v1, v2, s0
	s_waitcnt vmcnt(2)
	v_add_f32_e32 v0, v0, v47
	ds_write_b16 v190, v1 offset:19392
	v_mul_f32_e32 v1, 0x3fb8aa3b, v0
	v_exp_f32_e32 v1, v1
	v_mul_f32_e32 v2, 0xbfb8aa3b, v0
	v_exp_f32_e32 v2, v2
	v_lshlrev_b32_e32 v3, 16, v31
	v_mul_f32_e32 v1, v1, v3
	v_lshlrev_b32_e32 v3, 16, v41
	v_mul_f32_e32 v2, v2, v3
	v_cvt_pk_bf16_f32 v1, v1, s0
	ds_write_b16 v190, v1 offset:10320
	v_cvt_pk_bf16_f32 v1, v2, s0
	s_waitcnt vmcnt(1)
	v_add_f32_e32 v0, v0, v48
	ds_write_b16 v190, v1 offset:19536
	v_mul_f32_e32 v1, 0x3fb8aa3b, v0
	v_exp_f32_e32 v1, v1
	v_mul_f32_e32 v2, 0xbfb8aa3b, v0
	v_exp_f32_e32 v2, v2
	s_waitcnt vmcnt(0)
	v_add_f32_e32 v197, v0, v4
	v_mul_f32_e32 v0, 0x3fb8aa3b, v197
	v_lshlrev_b32_e32 v3, 16, v32
	v_exp_f32_e32 v196, v0
	v_mul_f32_e32 v0, 0xbfb8aa3b, v197
	v_mul_f32_e32 v1, v1, v3
	v_lshlrev_b32_e32 v3, 16, v42
	v_exp_f32_e32 v0, v0
	v_mul_f32_e32 v2, v2, v3
	v_cvt_pk_bf16_f32 v1, v1, s0
	ds_write_b16 v190, v1 offset:10464
	v_cvt_pk_bf16_f32 v1, v2, s0
	ds_write_b16 v190, v1 offset:19680
	v_lshlrev_b32_e32 v1, 16, v33
	v_lshlrev_b32_e32 v2, 16, v6
	v_mul_f32_e32 v1, v196, v1
	v_mul_f32_e32 v0, v0, v2
	v_cvt_pk_bf16_f32 v1, v1, s0
	v_cvt_pk_bf16_f32 v0, v0, s0
	ds_write_b16 v190, v1 offset:10608
	ds_write_b16 v190, v0 offset:19824
	ds_write_b16 v190, v93 offset:10752
	ds_write_b16 v190, v93 offset:19968
	ds_write_b16 v190, v93 offset:10896
	ds_write_b16 v190, v93 offset:20112
	ds_write_b16 v190, v93 offset:11040
	ds_write_b16 v190, v93 offset:20256
	ds_write_b16 v190, v93 offset:11184
	ds_write_b16 v190, v93 offset:20400
	ds_write_b16 v190, v93 offset:11328
	ds_write_b16 v190, v93 offset:20544
	ds_write_b16 v190, v93 offset:11472
	ds_write_b16 v190, v93 offset:20688
	ds_write_b16 v190, v93 offset:11616
	ds_write_b16 v190, v93 offset:20832
	ds_write_b16 v190, v93 offset:11760
	ds_write_b16 v190, v93 offset:20976
	ds_write_b16 v190, v93 offset:11904
	ds_write_b16 v190, v93 offset:21120
	ds_write_b16 v190, v93 offset:12048
	ds_write_b16 v190, v93 offset:21264
	ds_write_b16 v190, v93 offset:12192
	ds_write_b16 v190, v93 offset:21408
	ds_write_b16 v190, v93 offset:12336
	ds_write_b16 v190, v93 offset:21552
	ds_write_b16 v190, v93 offset:12480
	ds_write_b16 v190, v93 offset:21696
	ds_write_b16 v190, v93 offset:12624
	ds_write_b16 v190, v93 offset:21840
	ds_write_b16 v190, v93 offset:12768
	ds_write_b16 v190, v93 offset:21984
	ds_write_b16 v190, v93 offset:12912
	ds_write_b16 v190, v93 offset:22128
	s_waitcnt lgkmcnt(0)
; #define LAS __attribute__((address_space(3)))
; DI unsigned pk2(float a, float b) { f32x2 v = {a, b}; bf2v r = __builtin_convertvector(v, bf2v); return __builtin_bit_cast(unsigned, r); }
; #define MFMA32(a, b, c) __builtin_amdgcn_mfma_f32_32x32x16_bf16((a), (b), (c), 0, 0, 0)
; #define LDS_WAIT() asm volatile("s_waitcnt lgkmcnt(0)" ::: "memory")
; template <bool SAMPLE>
; DI void gla_out(const Params& p, int item, int tbsel, LAS unsigned char* wl, int lane) {
;     ...
;     LDS_WAIT();
;     {
;         bf16x8 bq[4];
; #pragma unroll
;         for (int kk = 0; kk < 4; ++kk) bq[kk] = *(const LAS bf16x8*)(Qs + (32 * tb + qi) * 144 + (16 * kk + 8 * hh) * 2);
;         f32x16 o[4];
; #pragma unroll
;         for (int dvb = 0; dvb < 4; ++dvb)
; #pragma unroll
;             for (int r = 0; r < 16; ++r) o[dvb][r] = 0.f;
; #pragma unroll
;         for (int dvb = 0; dvb < 4; ++dvb)
; #pragma unroll
;             for (int kk = 0; kk < 4; ++kk) {
;                 bf16x8 a;
;                 if (!SAMPLE) {
;                     a = sa[dvb][kk];
;                 } else {
;                     const float* sp = p.state_gla + (size_t)item * 8192 + (size_t)(16 * kk + 8 * hh) * 128 + 32 * dvb + qi;
;                     u32x4 w; w.x = pk2(sp[0], sp[128]); w.y = pk2(sp[256], sp[384]); w.z = pk2(sp[512], sp[640]); w.w = pk2(sp[768], sp[896]);
;                     a = __builtin_bit_cast(bf16x8, w);
;                 }
;                 o[dvb] = MFMA32(a, bq[kk], o[dvb]);
;                 if (SAMPLE) asm volatile("" ::: "memory");
;             }
	v_lshl_add_u64 v[0:1], v[160:161], 0, s[22:23]
	ds_read_b128 v[64:67], v202 offset:8448
	ds_read_b128 v[88:91], v202 offset:8480
	ds_read_b128 v[84:87], v202 offset:8512
	ds_read_b128 v[80:83], v202 offset:8544
	global_load_dword v8, v[0:1], off
	global_load_dword v9, v[0:1], off offset:512
	global_load_dword v10, v[0:1], off offset:1024
	global_load_dword v11, v[0:1], off offset:1536
	global_load_dword v12, v[0:1], off offset:2048
	global_load_dword v13, v[0:1], off offset:2560
	global_load_dword v14, v[0:1], off offset:3072
	global_load_dword v15, v[0:1], off offset:3584
	v_lshl_add_u64 v[2:3], v[162:163], 0, s[22:23]
	global_load_dword v16, v[2:3], off
	global_load_dword v17, v[2:3], off offset:512
	global_load_dword v18, v[2:3], off offset:1024
	global_load_dword v19, v[2:3], off offset:1536
	global_load_dword v20, v[2:3], off offset:2048
	global_load_dword v21, v[2:3], off offset:2560
	global_load_dword v22, v[2:3], off offset:3072
	global_load_dword v23, v[2:3], off offset:3584
	v_lshl_add_u64 v[4:5], v[164:165], 0, s[22:23]
	global_load_dword v24, v[4:5], off
	global_load_dword v25, v[4:5], off offset:512
	global_load_dword v26, v[4:5], off offset:1024
	global_load_dword v27, v[4:5], off offset:1536
	global_load_dword v28, v[4:5], off offset:2048
	global_load_dword v29, v[4:5], off offset:2560
	global_load_dword v30, v[4:5], off offset:3072
	global_load_dword v31, v[4:5], off offset:3584
	v_lshl_add_u64 v[6:7], v[166:167], 0, s[22:23]
	global_load_dword v32, v[6:7], off
	global_load_dword v33, v[6:7], off offset:512
	global_load_dword v34, v[6:7], off offset:1024
	global_load_dword v35, v[6:7], off offset:1536
	global_load_dword v36, v[6:7], off offset:2048
	global_load_dword v37, v[6:7], off offset:2560
	global_load_dword v38, v[6:7], off offset:3072
	global_load_dword v39, v[6:7], off offset:3584
	global_load_dword v40, v[0:1], off offset:128
	global_load_dword v41, v[0:1], off offset:640
	global_load_dword v42, v[0:1], off offset:1152
	global_load_dword v43, v[0:1], off offset:1664
	global_load_dword v44, v[0:1], off offset:2176
	global_load_dword v45, v[0:1], off offset:2688
	global_load_dword v46, v[0:1], off offset:3200
	global_load_dword v47, v[0:1], off offset:3712
	global_load_dword v68, v[2:3], off offset:128
	global_load_dword v69, v[2:3], off offset:640
	global_load_dword v70, v[2:3], off offset:1152
	global_load_dword v71, v[2:3], off offset:1664
	global_load_dword v72, v[2:3], off offset:2176
	global_load_dword v73, v[2:3], off offset:2688
	global_load_dword v74, v[2:3], off offset:3200
	global_load_dword v75, v[2:3], off offset:3712
	global_load_dword v76, v[4:5], off offset:128
	global_load_dword v77, v[4:5], off offset:640
	global_load_dword v78, v[4:5], off offset:1152
	global_load_dword v79, v[4:5], off offset:1664
	global_load_dword v198, v[4:5], off offset:2176
	global_load_dword v199, v[4:5], off offset:2688
	global_load_dword v200, v[4:5], off offset:3200
	global_load_dword v201, v[4:5], off offset:3712
	s_waitcnt vmcnt(54)
	v_cvt_pk_bf16_f32 v8, v8, v9
	s_waitcnt vmcnt(52)
	v_cvt_pk_bf16_f32 v9, v10, v11
	s_waitcnt vmcnt(50)
	v_cvt_pk_bf16_f32 v10, v12, v13
	s_waitcnt vmcnt(48)
	v_cvt_pk_bf16_f32 v11, v14, v15
	s_waitcnt lgkmcnt(3)
	s_nop 0
	v_mfma_f32_32x32x16_bf16 v[48:63], v[8:11], v[64:67], 0
	s_waitcnt vmcnt(46)
	v_cvt_pk_bf16_f32 v8, v16, v17
	s_waitcnt vmcnt(44)
	v_cvt_pk_bf16_f32 v9, v18, v19
	s_waitcnt vmcnt(42)
	v_cvt_pk_bf16_f32 v10, v20, v21
	s_waitcnt vmcnt(40)
	v_cvt_pk_bf16_f32 v11, v22, v23
	s_waitcnt lgkmcnt(2)
	s_nop 0
	v_mfma_f32_32x32x16_bf16 v[48:63], v[8:11], v[88:91], v[48:63]
	s_waitcnt vmcnt(38)
	v_cvt_pk_bf16_f32 v8, v24, v25
	s_waitcnt vmcnt(36)
	v_cvt_pk_bf16_f32 v9, v26, v27
	s_waitcnt vmcnt(34)
	v_cvt_pk_bf16_f32 v10, v28, v29
	s_waitcnt vmcnt(32)
	v_cvt_pk_bf16_f32 v11, v30, v31
	s_waitcnt lgkmcnt(1)
	s_nop 0
	v_mfma_f32_32x32x16_bf16 v[48:63], v[8:11], v[84:87], v[48:63]
	s_waitcnt vmcnt(30)
	v_cvt_pk_bf16_f32 v8, v32, v33
	s_waitcnt vmcnt(28)
	v_cvt_pk_bf16_f32 v9, v34, v35
	s_waitcnt vmcnt(26)
	v_cvt_pk_bf16_f32 v10, v36, v37
	s_waitcnt vmcnt(24)
	v_cvt_pk_bf16_f32 v11, v38, v39
	global_load_dword v12, v[6:7], off offset:128
	global_load_dword v13, v[6:7], off offset:640
	global_load_dword v14, v[6:7], off offset:1152
	global_load_dword v15, v[6:7], off offset:1664
	global_load_dword v32, v[6:7], off offset:2176
	global_load_dword v33, v[6:7], off offset:2688
	global_load_dword v34, v[6:7], off offset:3200
	global_load_dword v35, v[6:7], off offset:3712
	s_waitcnt lgkmcnt(0)
	v_mfma_f32_32x32x16_bf16 v[48:63], v[8:11], v[80:83], v[48:63]
	s_waitcnt vmcnt(30)
	v_cvt_pk_bf16_f32 v8, v40, v41
	s_waitcnt vmcnt(28)
	v_cvt_pk_bf16_f32 v9, v42, v43
	global_load_dword v36, v[0:1], off offset:256
	global_load_dword v37, v[0:1], off offset:768
	global_load_dword v38, v[0:1], off offset:1280
	global_load_dword v39, v[0:1], off offset:1792
	global_load_dword v40, v[0:1], off offset:2304
	global_load_dword v41, v[0:1], off offset:2816
	global_load_dword v42, v[0:1], off offset:3328
	global_load_dword v43, v[0:1], off offset:3840
	s_waitcnt vmcnt(34)
	v_cvt_pk_bf16_f32 v10, v44, v45
	s_waitcnt vmcnt(32)
	v_cvt_pk_bf16_f32 v11, v46, v47
	s_nop 1
	v_mfma_f32_32x32x16_bf16 v[16:31], v[8:11], v[64:67], 0
	s_waitcnt vmcnt(30)
	v_cvt_pk_bf16_f32 v8, v68, v69
	s_waitcnt vmcnt(28)
	v_cvt_pk_bf16_f32 v9, v70, v71
	s_waitcnt vmcnt(26)
	v_cvt_pk_bf16_f32 v10, v72, v73
	s_waitcnt vmcnt(24)
; #define LAS __attribute__((address_space(3)))
; DI unsigned pk2(float a, float b) { f32x2 v = {a, b}; bf2v r = __builtin_convertvector(v, bf2v); return __builtin_bit_cast(unsigned, r); }
; #define MFMA32(a, b, c) __builtin_amdgcn_mfma_f32_32x32x16_bf16((a), (b), (c), 0, 0, 0)
; template <bool SAMPLE>
; DI void gla_out(const Params& p, int item, int tbsel, LAS unsigned char* wl, int lane) {
;     ...
;         for (int dvb = 0; dvb < 4; ++dvb)
; #pragma unroll
;             for (int kk = 0; kk < 4; ++kk) {
;                 bf16x8 a;
;                 if (!SAMPLE) {
;                     a = sa[dvb][kk];
;                 } else {
;                     const float* sp = p.state_gla + (size_t)item * 8192 + (size_t)(16 * kk + 8 * hh) * 128 + 32 * dvb + qi;
;                     u32x4 w; w.x = pk2(sp[0], sp[128]); w.y = pk2(sp[256], sp[384]); w.z = pk2(sp[512], sp[640]); w.w = pk2(sp[768], sp[896]);
;                     a = __builtin_bit_cast(bf16x8, w);
;                 }
;                 o[dvb] = MFMA32(a, bq[kk], o[dvb]);
;                 if (SAMPLE) asm volatile("" ::: "memory");
;             }
; #pragma unroll
;         for (int sbk = 0; sbk < (SAMPLE ? 1 : 2); ++sbk) if (sbk <= tb) {
;             f32x16 st;
; #pragma unroll
;             for (int r = 0; r < 16; ++r) st[r] = 0.f;
; #pragma unroll
;             for (int kk = 0; kk < 4; ++kk) { const bf16x8 ak = *(const LAS bf16x8*)(Ks + (32 * sbk + qi) * 144 + (16 * kk + 8 * hh) * 2); st = MFMA32(ak, bq[kk], st); }
	v_cvt_pk_bf16_f32 v11, v74, v75
	global_load_dword v68, v[2:3], off offset:256
	global_load_dword v69, v[2:3], off offset:768
	global_load_dword v70, v[2:3], off offset:1280
	global_load_dword v71, v[2:3], off offset:1792
	global_load_dword v72, v[2:3], off offset:2304
	global_load_dword v73, v[2:3], off offset:2816
	global_load_dword v74, v[2:3], off offset:3328
	global_load_dword v75, v[2:3], off offset:3840
	v_mfma_f32_32x32x16_bf16 v[16:31], v[8:11], v[88:91], v[16:31]
	s_waitcnt vmcnt(30)
	v_cvt_pk_bf16_f32 v8, v76, v77
	s_waitcnt vmcnt(28)
	v_cvt_pk_bf16_f32 v9, v78, v79
	s_waitcnt vmcnt(26)
	v_cvt_pk_bf16_f32 v10, v198, v199
	s_waitcnt vmcnt(24)
	v_cvt_pk_bf16_f32 v11, v200, v201
	global_load_dword v76, v[4:5], off offset:256
	global_load_dword v77, v[4:5], off offset:768
	global_load_dword v78, v[4:5], off offset:1280
	global_load_dword v79, v[4:5], off offset:1792
	global_load_dword v198, v[4:5], off offset:2304
	global_load_dword v199, v[4:5], off offset:2816
	global_load_dword v200, v[4:5], off offset:3328
	global_load_dword v201, v[4:5], off offset:3840
	global_load_dword v204, v[6:7], off offset:256
	global_load_dword v205, v[6:7], off offset:768
	global_load_dword v206, v[6:7], off offset:1280
	global_load_dword v207, v[6:7], off offset:1792
	global_load_dword v208, v[6:7], off offset:2304
	global_load_dword v209, v[6:7], off offset:2816
	global_load_dword v210, v[6:7], off offset:3328
	global_load_dword v211, v[6:7], off offset:3840
	global_load_dword v212, v[0:1], off offset:384
	global_load_dword v213, v[0:1], off offset:896
	global_load_dword v214, v[0:1], off offset:1408
	global_load_dword v215, v[0:1], off offset:1920
	global_load_dword v216, v[0:1], off offset:2432
	global_load_dword v217, v[0:1], off offset:2944
	global_load_dword v218, v[0:1], off offset:3456
	global_load_dword v219, v[0:1], off offset:3968
	global_load_dword v220, v[2:3], off offset:384
	global_load_dword v221, v[2:3], off offset:896
	global_load_dword v222, v[2:3], off offset:1408
	global_load_dword v223, v[2:3], off offset:1920
	global_load_dword v224, v[2:3], off offset:2432
	global_load_dword v225, v[2:3], off offset:2944
	global_load_dword v226, v[2:3], off offset:3456
	global_load_dword v227, v[2:3], off offset:3968
	global_load_dword v228, v[4:5], off offset:384
	global_load_dword v229, v[4:5], off offset:896
	global_load_dword v230, v[4:5], off offset:1408
	global_load_dword v231, v[4:5], off offset:1920
	global_load_dword v232, v[4:5], off offset:2432
	global_load_dword v233, v[4:5], off offset:2944
	global_load_dword v234, v[4:5], off offset:3456
	global_load_dword v235, v[4:5], off offset:3968
	global_load_dword v236, v[6:7], off offset:384
	global_load_dword v237, v[6:7], off offset:896
	global_load_dword v238, v[6:7], off offset:1408
	global_load_dword v239, v[6:7], off offset:1920
	global_load_dword v240, v[6:7], off offset:2432
	global_load_dword v241, v[6:7], off offset:2944
	global_load_dword v242, v[6:7], off offset:3456
	global_load_dword v243, v[6:7], off offset:3968
	v_mfma_f32_32x32x16_bf16 v[16:31], v[8:11], v[84:87], v[16:31]
	s_waitcnt vmcnt(62)
	v_cvt_pk_bf16_f32 v0, v12, v13
	v_cvt_pk_bf16_f32 v1, v14, v15
	v_cvt_pk_bf16_f32 v2, v32, v33
	v_cvt_pk_bf16_f32 v3, v34, v35
	s_nop 1
	v_mfma_f32_32x32x16_bf16 v[16:31], v[0:3], v[80:83], v[16:31]
	v_cvt_pk_bf16_f32 v0, v36, v37
	s_waitcnt vmcnt(60)
	v_cvt_pk_bf16_f32 v1, v38, v39
	s_waitcnt vmcnt(58)
	v_cvt_pk_bf16_f32 v2, v40, v41
	s_waitcnt vmcnt(56)
	v_cvt_pk_bf16_f32 v3, v42, v43
	s_nop 1
	v_mfma_f32_32x32x16_bf16 v[32:47], v[0:3], v[64:67], 0
	s_waitcnt vmcnt(54)
	v_cvt_pk_bf16_f32 v0, v68, v69
	s_waitcnt vmcnt(52)
	v_cvt_pk_bf16_f32 v1, v70, v71
	s_waitcnt vmcnt(50)
	v_cvt_pk_bf16_f32 v2, v72, v73
	s_waitcnt vmcnt(48)
	v_cvt_pk_bf16_f32 v3, v74, v75
	s_waitcnt vmcnt(22)
	v_cvt_pk_bf16_f32 v68, v220, v221
	v_mfma_f32_32x32x16_bf16 v[32:47], v[0:3], v[88:91], v[32:47]
	v_cvt_pk_bf16_f32 v0, v76, v77
	v_cvt_pk_bf16_f32 v1, v78, v79
	v_cvt_pk_bf16_f32 v2, v198, v199
	v_cvt_pk_bf16_f32 v3, v200, v201
	s_waitcnt vmcnt(20)
	v_cvt_pk_bf16_f32 v69, v222, v223
	s_waitcnt vmcnt(18)
	v_cvt_pk_bf16_f32 v70, v224, v225
	s_waitcnt vmcnt(16)
	v_cvt_pk_bf16_f32 v71, v226, v227
	v_mfma_f32_32x32x16_bf16 v[32:47], v[0:3], v[84:87], v[32:47]
	v_cvt_pk_bf16_f32 v0, v204, v205
	v_cvt_pk_bf16_f32 v1, v206, v207
	v_cvt_pk_bf16_f32 v2, v208, v209
	v_cvt_pk_bf16_f32 v3, v210, v211
	s_nop 1
	v_mfma_f32_32x32x16_bf16 v[32:47], v[0:3], v[80:83], v[32:47]
	v_cvt_pk_bf16_f32 v0, v212, v213
	v_cvt_pk_bf16_f32 v1, v214, v215
	v_cvt_pk_bf16_f32 v2, v216, v217
	v_cvt_pk_bf16_f32 v3, v218, v219
	s_nop 1
	v_mfma_f32_32x32x16_bf16 v[0:15], v[0:3], v[64:67], 0
	v_mfma_f32_32x32x16_bf16 v[0:15], v[68:71], v[88:91], v[0:15]
	s_waitcnt vmcnt(14)
	v_cvt_pk_bf16_f32 v68, v228, v229
	s_waitcnt vmcnt(12)
	v_cvt_pk_bf16_f32 v69, v230, v231
	s_waitcnt vmcnt(10)
	v_cvt_pk_bf16_f32 v70, v232, v233
	s_waitcnt vmcnt(8)
	v_cvt_pk_bf16_f32 v71, v234, v235
	s_nop 1
	v_mfma_f32_32x32x16_bf16 v[0:15], v[68:71], v[84:87], v[0:15]
	s_waitcnt vmcnt(6)
	v_cvt_pk_bf16_f32 v68, v236, v237
	s_waitcnt vmcnt(4)
	v_cvt_pk_bf16_f32 v69, v238, v239
	s_waitcnt vmcnt(2)
	v_cvt_pk_bf16_f32 v70, v240, v241
	s_waitcnt vmcnt(0)
	v_cvt_pk_bf16_f32 v71, v242, v243
	s_nop 1
	v_mfma_f32_32x32x16_bf16 v[0:15], v[68:71], v[80:83], v[0:15]
	ds_read_b128 v[68:71], v202 offset:17664
	ds_read_b128 v[198:201], v202 offset:17696
	ds_read_b128 v[204:207], v202 offset:17728
	s_waitcnt lgkmcnt(2)
	v_mfma_f32_32x32x16_bf16 v[64:79], v[68:71], v[64:67], 0
	s_waitcnt lgkmcnt(1)
; #define LAS __attribute__((address_space(3)))
; DI unsigned pk2(float a, float b) { f32x2 v = {a, b}; bf2v r = __builtin_convertvector(v, bf2v); return __builtin_bit_cast(unsigned, r); }
; #define MFMA32(a, b, c) __builtin_amdgcn_mfma_f32_32x32x16_bf16((a), (b), (c), 0, 0, 0)
; template <bool SAMPLE>
; DI void gla_out(const Params& p, int item, int tbsel, LAS unsigned char* wl, int lane) {
;     ...
;             for (int kk = 0; kk < 4; ++kk) { const bf16x8 ak = *(const LAS bf16x8*)(Ks + (32 * sbk + qi) * 144 + (16 * kk + 8 * hh) * 2); st = MFMA32(ak, bq[kk], st); }
;             if (sbk == tb) {
; #pragma unroll
;                 for (int r = 0; r < 16; ++r) if ((r & 3) + 8 * (r >> 2) + 4 * hh > qi) st[r] = 0.f;
;             }
; #pragma unroll
;             for (int ks = 0; ks < (SAMPLE ? 1 : 2); ++ks) {
;                 u32x4 pw; pw.x = pk2(st[8 * ks], st[8 * ks + 1]); pw.y = pk2(st[8 * ks + 2], st[8 * ks + 3]); pw.z = pk2(st[8 * ks + 4], st[8 * ks + 5]); pw.w = pk2(st[8 * ks + 6], st[8 * ks + 7]);
;                 const bf16x8 pb = __builtin_bit_cast(bf16x8, pw);
; #pragma unroll
;                 for (int dvb = 0; dvb < 4; ++dvb) {
;                     u32x2 v0, v1;
;                     if (SAMPLE) { const bf16_t* vp = (const bf16_t*)(ws + OFF_VBTS) + (size_t)(sb * 512 + h * 128 + 32 * dvb + qi) * 16 + 4 * hh; v0 = *(const u32x2*)vp; v1 = *(const u32x2*)(vp + 8); }
;                     else { v0 = vf[sbk][ks][dvb][0]; v1 = vf[sbk][ks][dvb][1]; }
;                     u32x4 aw; aw.x = v0.x; aw.y = v0.y; aw.z = v1.x; aw.w = v1.y;
;                     o[dvb] = MFMA32(__builtin_bit_cast(bf16x8, aw), pb, o[dvb]);
;                 }
;             }
;         }
;         float ss = 0.f;
; #pragma unroll
;         for (int dvb = 0; dvb < 4; ++dvb)
; #pragma unroll
;             for (int r = 0; r < 16; ++r) ss += o[dvb][r] * o[dvb][r];
;         ss += __shfl_xor(ss, 32);
;         const float rstd = rsqrtf(ss * (1.f / 128.f) + EPS);
;         int lz = 0; asm volatile("" : "+v"(lz));
;         if (!SAMPLE || qi < 16) {
	v_mfma_f32_32x32x16_bf16 v[64:79], v[198:201], v[88:91], v[64:79]
	v_lshl_or_b32 v90, s38, 9, v192
	v_ashrrev_i32_e32 v91, 31, v90
	v_lshlrev_b64 v[88:89], 5, v[90:91]
	v_lshl_add_u64 v[200:201], v[168:169], 0, v[88:89]
	global_load_dwordx2 v[198:199], v[200:201], off
	s_nop 0
	global_load_dwordx2 v[200:201], v[200:201], off offset:16
	ds_read_b128 v[208:211], v202 offset:17760
	s_waitcnt lgkmcnt(1)
	v_mfma_f32_32x32x16_bf16 v[64:79], v[204:207], v[84:87], v[64:79]
	v_or_b32_e32 v84, 32, v90
	v_ashrrev_i32_e32 v85, 31, v84
	v_lshlrev_b64 v[84:85], 5, v[84:85]
	v_lshl_add_u64 v[86:87], v[168:169], 0, v[84:85]
	global_load_dwordx2 v[204:205], v[86:87], off
	global_load_dwordx2 v[206:207], v[86:87], off offset:16
	s_waitcnt lgkmcnt(0)
	v_mfma_f32_32x32x16_bf16 v[64:79], v[208:211], v[80:83], v[64:79]
	s_nop 11
	v_cndmask_b32_e64 v72, v64, 0, s[4:5]
	v_cndmask_b32_e64 v64, v72, v64, s[6:7]
	v_cndmask_b32_e64 v65, 0, v65, s[6:7]
	v_cndmask_b32_e64 v72, v68, 0, s[12:13]
	v_cvt_pk_bf16_f32 v68, v64, v65
	v_or_b32_e32 v64, 64, v90
	v_cndmask_b32_e64 v66, v66, 0, s[8:9]
	v_cndmask_b32_e64 v67, v67, 0, s[10:11]
	v_ashrrev_i32_e32 v65, 31, v64
	v_cndmask_b32_e64 v73, v69, 0, s[14:15]
	v_cvt_pk_bf16_f32 v69, v66, v67
	v_lshlrev_b64 v[66:67], 5, v[64:65]
	v_cndmask_b32_e64 v74, v70, 0, s[16:17]
	v_cndmask_b32_e64 v71, v71, 0, s[18:19]
	v_lshl_add_u64 v[64:65], v[168:169], 0, v[66:67]
	v_cvt_pk_bf16_f32 v70, v72, v73
	v_cvt_pk_bf16_f32 v71, v74, v71
	global_load_dwordx2 v[72:73], v[64:65], off
	global_load_dwordx2 v[74:75], v[64:65], off offset:16
	v_or_b32_e32 v64, 0x60, v90
	v_ashrrev_i32_e32 v65, 31, v64
	v_lshlrev_b64 v[64:65], 5, v[64:65]
	v_lshl_add_u64 v[78:79], v[168:169], 0, v[64:65]
	global_load_dwordx2 v[76:77], v[78:79], off
	s_nop 0
	global_load_dwordx2 v[78:79], v[78:79], off offset:16
	s_waitcnt vmcnt(6)
	v_mfma_f32_32x32x16_bf16 v[48:63], v[198:201], v[68:71], v[48:63]
	s_waitcnt vmcnt(0)
	v_mfma_f32_32x32x16_bf16 v[0:15], v[76:79], v[68:71], v[0:15]
	s_nop 9
	v_mul_f32_e32 v78, v49, v49
	v_fmac_f32_e32 v78, v48, v48
	v_fmac_f32_e32 v78, v50, v50
	v_fmac_f32_e32 v78, v51, v51
	v_fmac_f32_e32 v78, v52, v52
	v_fmac_f32_e32 v78, v53, v53
	v_fmac_f32_e32 v78, v54, v54
	v_fmac_f32_e32 v78, v55, v55
	v_mfma_f32_32x32x16_bf16 v[16:31], v[204:207], v[68:71], v[16:31]
	v_fmac_f32_e32 v78, v56, v56
	v_fmac_f32_e32 v78, v57, v57
	v_fmac_f32_e32 v78, v58, v58
	v_fmac_f32_e32 v78, v59, v59
	v_fmac_f32_e32 v78, v60, v60
	v_fmac_f32_e32 v78, v61, v61
	v_fmac_f32_e32 v78, v62, v62
	v_fmac_f32_e32 v78, v63, v63
	s_nop 3
	v_fmac_f32_e32 v78, v16, v16
	v_fmac_f32_e32 v78, v17, v17
	v_fmac_f32_e32 v78, v18, v18
	v_fmac_f32_e32 v78, v19, v19
	v_fmac_f32_e32 v78, v20, v20
	v_fmac_f32_e32 v78, v21, v21
	v_fmac_f32_e32 v78, v22, v22
	v_fmac_f32_e32 v78, v23, v23
	v_mfma_f32_32x32x16_bf16 v[32:47], v[72:75], v[68:71], v[32:47]
	v_fmac_f32_e32 v78, v24, v24
	v_fmac_f32_e32 v78, v25, v25
	v_fmac_f32_e32 v78, v26, v26
	v_fmac_f32_e32 v78, v27, v27
	v_fmac_f32_e32 v78, v28, v28
	v_fmac_f32_e32 v78, v29, v29
	v_fmac_f32_e32 v78, v30, v30
	v_fmac_f32_e32 v78, v31, v31
	s_nop 3
	v_fmac_f32_e32 v78, v32, v32
	v_fmac_f32_e32 v78, v33, v33
	v_fmac_f32_e32 v78, v34, v34
	v_fmac_f32_e32 v78, v35, v35
	v_fmac_f32_e32 v78, v36, v36
	v_fmac_f32_e32 v78, v37, v37
	v_fmac_f32_e32 v78, v38, v38
	v_fmac_f32_e32 v78, v39, v39
	v_fmac_f32_e32 v78, v40, v40
	v_fmac_f32_e32 v78, v41, v41
	v_fmac_f32_e32 v78, v42, v42
	v_fmac_f32_e32 v78, v43, v43
	v_fmac_f32_e32 v78, v44, v44
	v_fmac_f32_e32 v78, v45, v45
	v_fmac_f32_e32 v78, v46, v46
	v_fmac_f32_e32 v78, v47, v47
	v_fmac_f32_e32 v78, v0, v0
	v_fmac_f32_e32 v78, v1, v1
	v_fmac_f32_e32 v78, v2, v2
	v_fmac_f32_e32 v78, v3, v3
	v_fmac_f32_e32 v78, v4, v4
	v_fmac_f32_e32 v78, v5, v5
	v_pk_mul_f32 v[76:77], v[6:7], v[6:7]
	v_pk_mul_f32 v[74:75], v[8:9], v[8:9]
	v_add_f32_e32 v76, v76, v78
	v_add_f32_e32 v76, v77, v76
	v_add_f32_e32 v74, v74, v76
	v_pk_mul_f32 v[72:73], v[10:11], v[10:11]
	v_add_f32_e32 v74, v75, v74
	v_add_f32_e32 v72, v72, v74
	v_pk_mul_f32 v[70:71], v[12:13], v[12:13]
	v_add_f32_e32 v72, v73, v72
	v_add_f32_e32 v70, v70, v72
	v_pk_mul_f32 v[68:69], v[14:15], v[14:15]
	v_add_f32_e32 v70, v71, v70
	v_add_f32_e32 v68, v68, v70
	v_add_f32_e32 v72, v69, v68
	v_cndmask_b32_e32 v68, v187, v188, vcc
	v_lshlrev_b32_e32 v68, 2, v68
	ds_bpermute_b32 v73, v68, v72
	v_mov_b32_e32 v68, 0
	s_and_saveexec_b64 s[22:23], s[20:21]
	s_cbranch_execz .LBB0_1008
; DI unsigned pk2(float a, float b) { f32x2 v = {a, b}; bf2v r = __builtin_convertvector(v, bf2v); return __builtin_bit_cast(unsigned, r); }
; DI float bflo(unsigned w) { return __uint_as_float(w << 16); }
; DI float bfhi(unsigned w) { return __uint_as_float(w & 0xffff0000u); }
; template <bool SAMPLE>
; DI void gla_out(const Params& p, int item, int tbsel, LAS unsigned char* wl, int lane) {
;     ...
;         const float rstd = rsqrtf(ss * (1.f / 128.f) + EPS);
;         int lz = 0; asm volatile("" : "+v"(lz));
;         if (!SAMPLE || qi < 16) {
;             bf16_t* zr = (bf16_t*)(ws + OFF_ZB) + (size_t)(t0 + 32 * tb + qi) * 512 + h * 128 + 4 * hh;
; #pragma unroll
;             for (int dvb = 0; dvb < 4; ++dvb)
; #pragma unroll
;                 for (int g = 0; g < 4; ++g) {
;                     const int dv = 32 * dvb + 8 * g;
;                     const f32x4 gg = *(const f32x4*)(p.g_gla_out + dv + 4 * hh + lz);
;                     const u32x2 z = *(const u32x2*)(zr + dv); u32x2 w;
;                     w.x = pk2(o[dvb][4 * g] * rstd * gg[0] * bflo(z.x), o[dvb][4 * g + 1] * rstd * gg[1] * bfhi(z.x));
;                     w.y = pk2(o[dvb][4 * g + 2] * rstd * gg[2] * bflo(z.y), o[dvb][4 * g + 3] * rstd * gg[3] * bfhi(z.y));
;                     *(u32x2*)(zr + dv) = w;
;                 }
	v_or_b32_e32 v70, s72, v144
	v_ashrrev_i32_e32 v71, 31, v70
	v_lshlrev_b64 v[78:79], 10, v[70:71]
	v_ashrrev_i32_e32 v69, 31, v68
	v_lshl_add_u64 v[70:71], v[68:69], 2, v[170:171]
	v_lshl_add_u64 v[68:69], v[178:179], 0, v[78:79]
	global_load_dwordx2 v[236:237], v[68:69], off
	global_load_dwordx2 v[238:239], v[68:69], off offset:16
	global_load_dwordx2 v[240:241], v[68:69], off offset:32
	global_load_dwordx2 v[242:243], v[68:69], off offset:48
	global_load_dwordx2 v[244:245], v[68:69], off offset:64
	global_load_dwordx2 v[246:247], v[68:69], off offset:80
	global_load_dwordx2 v[248:249], v[68:69], off offset:96
	global_load_dwordx2 v[250:251], v[68:69], off offset:112
	global_load_dwordx4 v[204:207], v[70:71], off
	global_load_dwordx4 v[208:211], v[70:71], off offset:32
	global_load_dwordx4 v[212:215], v[70:71], off offset:64
	global_load_dwordx4 v[216:219], v[70:71], off offset:96
	global_load_dwordx4 v[220:223], v[70:71], off offset:128
	global_load_dwordx4 v[224:227], v[70:71], off offset:160
	global_load_dwordx4 v[228:231], v[70:71], off offset:192
	global_load_dwordx4 v[232:235], v[70:71], off offset:224
	s_waitcnt lgkmcnt(0)
	v_add_f32_e32 v72, v72, v73
	v_fmamk_f32 v72, v72, 0x3c000000, v193
	v_mul_f32_e32 v73, 0x4b800000, v72
	v_cmp_gt_f32_e32 vcc, s48, v72
	s_nop 1
	v_cndmask_b32_e32 v72, v72, v73, vcc
	v_rsq_f32_e32 v72, v72
	s_nop 0
	v_mul_f32_e32 v73, 0x45800000, v72
	v_cndmask_b32_e32 v72, v72, v73, vcc
	v_pk_mul_f32 v[48:49], v[48:49], v[72:73] op_sel_hi:[1,0]
	v_pk_mul_f32 v[50:51], v[50:51], v[72:73] op_sel_hi:[1,0]
	s_waitcnt vmcnt(7)
	v_lshlrev_b32_e32 v74, 16, v236
	v_and_b32_e32 v75, 0xffff0000, v236
	v_lshlrev_b32_e32 v76, 16, v237
	v_and_b32_e32 v77, 0xffff0000, v237
	v_pk_mul_f32 v[48:49], v[48:49], v[204:205]
	v_pk_mul_f32 v[50:51], v[50:51], v[206:207]
	v_pk_mul_f32 v[48:49], v[48:49], v[74:75]
	v_pk_mul_f32 v[50:51], v[50:51], v[76:77]
	v_cvt_pk_bf16_f32 v48, v48, v49
	v_cvt_pk_bf16_f32 v49, v50, v51
	global_store_dwordx2 v[68:69], v[48:49], off
	v_pk_mul_f32 v[52:53], v[52:53], v[72:73] op_sel_hi:[1,0]
	v_pk_mul_f32 v[54:55], v[54:55], v[72:73] op_sel_hi:[1,0]
	s_waitcnt vmcnt(7)
	v_lshlrev_b32_e32 v74, 16, v238
	v_and_b32_e32 v75, 0xffff0000, v238
	v_lshlrev_b32_e32 v76, 16, v239
	v_and_b32_e32 v77, 0xffff0000, v239
	v_pk_mul_f32 v[52:53], v[52:53], v[208:209]
	v_pk_mul_f32 v[54:55], v[54:55], v[210:211]
	v_pk_mul_f32 v[52:53], v[52:53], v[74:75]
	v_pk_mul_f32 v[54:55], v[54:55], v[76:77]
	v_cvt_pk_bf16_f32 v52, v52, v53
	v_cvt_pk_bf16_f32 v53, v54, v55
	global_store_dwordx2 v[68:69], v[52:53], off offset:16
	v_pk_mul_f32 v[56:57], v[56:57], v[72:73] op_sel_hi:[1,0]
	v_pk_mul_f32 v[58:59], v[58:59], v[72:73] op_sel_hi:[1,0]
	s_waitcnt vmcnt(7)
	v_lshlrev_b32_e32 v74, 16, v240
	v_and_b32_e32 v75, 0xffff0000, v240
	v_lshlrev_b32_e32 v76, 16, v241
	v_and_b32_e32 v77, 0xffff0000, v241
	v_pk_mul_f32 v[56:57], v[56:57], v[212:213]
	v_pk_mul_f32 v[58:59], v[58:59], v[214:215]
	v_pk_mul_f32 v[56:57], v[56:57], v[74:75]
	v_pk_mul_f32 v[58:59], v[58:59], v[76:77]
	v_cvt_pk_bf16_f32 v56, v56, v57
	v_cvt_pk_bf16_f32 v57, v58, v59
	global_store_dwordx2 v[68:69], v[56:57], off offset:32
	v_pk_mul_f32 v[60:61], v[60:61], v[72:73] op_sel_hi:[1,0]
	v_pk_mul_f32 v[62:63], v[62:63], v[72:73] op_sel_hi:[1,0]
	s_waitcnt vmcnt(7)
	v_lshlrev_b32_e32 v74, 16, v242
	v_and_b32_e32 v75, 0xffff0000, v242
	v_lshlrev_b32_e32 v76, 16, v243
	v_and_b32_e32 v77, 0xffff0000, v243
	v_pk_mul_f32 v[60:61], v[60:61], v[216:217]
	v_pk_mul_f32 v[62:63], v[62:63], v[218:219]
	v_pk_mul_f32 v[60:61], v[60:61], v[74:75]
	v_pk_mul_f32 v[62:63], v[62:63], v[76:77]
	v_cvt_pk_bf16_f32 v60, v60, v61
	v_cvt_pk_bf16_f32 v61, v62, v63
	global_store_dwordx2 v[68:69], v[60:61], off offset:48
	v_pk_mul_f32 v[16:17], v[16:17], v[72:73] op_sel_hi:[1,0]
	v_pk_mul_f32 v[18:19], v[18:19], v[72:73] op_sel_hi:[1,0]
	s_waitcnt vmcnt(7)
	v_lshlrev_b32_e32 v74, 16, v244
	v_and_b32_e32 v75, 0xffff0000, v244
	v_lshlrev_b32_e32 v76, 16, v245
	v_and_b32_e32 v77, 0xffff0000, v245
	v_pk_mul_f32 v[16:17], v[16:17], v[220:221]
	v_pk_mul_f32 v[18:19], v[18:19], v[222:223]
	v_pk_mul_f32 v[16:17], v[16:17], v[74:75]
	v_pk_mul_f32 v[18:19], v[18:19], v[76:77]
	v_cvt_pk_bf16_f32 v16, v16, v17
	v_cvt_pk_bf16_f32 v17, v18, v19
	global_store_dwordx2 v[68:69], v[16:17], off offset:64
	v_pk_mul_f32 v[20:21], v[20:21], v[72:73] op_sel_hi:[1,0]
	v_pk_mul_f32 v[22:23], v[22:23], v[72:73] op_sel_hi:[1,0]
	s_waitcnt vmcnt(7)
	v_lshlrev_b32_e32 v74, 16, v246
	v_and_b32_e32 v75, 0xffff0000, v246
	v_lshlrev_b32_e32 v76, 16, v247
	v_and_b32_e32 v77, 0xffff0000, v247
	v_pk_mul_f32 v[20:21], v[20:21], v[224:225]
	v_pk_mul_f32 v[22:23], v[22:23], v[226:227]
	v_pk_mul_f32 v[20:21], v[20:21], v[74:75]
	v_pk_mul_f32 v[22:23], v[22:23], v[76:77]
	v_cvt_pk_bf16_f32 v20, v20, v21
	v_cvt_pk_bf16_f32 v21, v22, v23
	global_store_dwordx2 v[68:69], v[20:21], off offset:80
	v_pk_mul_f32 v[24:25], v[24:25], v[72:73] op_sel_hi:[1,0]
	v_pk_mul_f32 v[26:27], v[26:27], v[72:73] op_sel_hi:[1,0]
	s_waitcnt vmcnt(7)
	v_lshlrev_b32_e32 v74, 16, v248
	v_and_b32_e32 v75, 0xffff0000, v248
	v_lshlrev_b32_e32 v76, 16, v249
	v_and_b32_e32 v77, 0xffff0000, v249
	v_pk_mul_f32 v[24:25], v[24:25], v[228:229]
	v_pk_mul_f32 v[26:27], v[26:27], v[230:231]
	v_pk_mul_f32 v[24:25], v[24:25], v[74:75]
	v_pk_mul_f32 v[26:27], v[26:27], v[76:77]
	v_cvt_pk_bf16_f32 v24, v24, v25
	v_cvt_pk_bf16_f32 v25, v26, v27
	global_store_dwordx2 v[68:69], v[24:25], off offset:96
	v_pk_mul_f32 v[28:29], v[28:29], v[72:73] op_sel_hi:[1,0]
	v_pk_mul_f32 v[30:31], v[30:31], v[72:73] op_sel_hi:[1,0]
	s_waitcnt vmcnt(7)
; DI unsigned pk2(float a, float b) { f32x2 v = {a, b}; bf2v r = __builtin_convertvector(v, bf2v); return __builtin_bit_cast(unsigned, r); }
; DI float bflo(unsigned w) { return __uint_as_float(w << 16); }
; DI float bfhi(unsigned w) { return __uint_as_float(w & 0xffff0000u); }
; template <bool SAMPLE>
; DI void gla_out(const Params& p, int item, int tbsel, LAS unsigned char* wl, int lane) {
;     ...
;         if (!SAMPLE || qi < 16) {
;             bf16_t* zr = (bf16_t*)(ws + OFF_ZB) + (size_t)(t0 + 32 * tb + qi) * 512 + h * 128 + 4 * hh;
; #pragma unroll
;             for (int dvb = 0; dvb < 4; ++dvb)
; #pragma unroll
;                 for (int g = 0; g < 4; ++g) {
;                     const int dv = 32 * dvb + 8 * g;
;                     const f32x4 gg = *(const f32x4*)(p.g_gla_out + dv + 4 * hh + lz);
;                     const u32x2 z = *(const u32x2*)(zr + dv); u32x2 w;
;                     w.x = pk2(o[dvb][4 * g] * rstd * gg[0] * bflo(z.x), o[dvb][4 * g + 1] * rstd * gg[1] * bfhi(z.x));
;                     w.y = pk2(o[dvb][4 * g + 2] * rstd * gg[2] * bflo(z.y), o[dvb][4 * g + 3] * rstd * gg[3] * bfhi(z.y));
;                     *(u32x2*)(zr + dv) = w;
;                 }
;         }
	v_lshlrev_b32_e32 v74, 16, v250
	v_and_b32_e32 v75, 0xffff0000, v250
	v_lshlrev_b32_e32 v76, 16, v251
	v_and_b32_e32 v77, 0xffff0000, v251
	v_pk_mul_f32 v[28:29], v[28:29], v[232:233]
	v_pk_mul_f32 v[30:31], v[30:31], v[234:235]
	v_pk_mul_f32 v[28:29], v[28:29], v[74:75]
	v_pk_mul_f32 v[30:31], v[30:31], v[76:77]
	v_cvt_pk_bf16_f32 v28, v28, v29
	v_cvt_pk_bf16_f32 v29, v30, v31
	global_store_dwordx2 v[68:69], v[28:29], off offset:112
	global_load_dwordx2 v[236:237], v[68:69], off offset:128
	global_load_dwordx2 v[238:239], v[68:69], off offset:144
	global_load_dwordx2 v[240:241], v[68:69], off offset:160
	global_load_dwordx2 v[242:243], v[68:69], off offset:176
	global_load_dwordx2 v[244:245], v[68:69], off offset:192
	global_load_dwordx2 v[246:247], v[68:69], off offset:208
	global_load_dwordx2 v[248:249], v[68:69], off offset:224
	global_load_dwordx2 v[250:251], v[68:69], off offset:240
	global_load_dwordx4 v[204:207], v[70:71], off offset:256
	global_load_dwordx4 v[208:211], v[70:71], off offset:288
	global_load_dwordx4 v[212:215], v[70:71], off offset:320
	global_load_dwordx4 v[216:219], v[70:71], off offset:352
	global_load_dwordx4 v[220:223], v[70:71], off offset:384
	global_load_dwordx4 v[224:227], v[70:71], off offset:416
	global_load_dwordx4 v[228:231], v[70:71], off offset:448
	global_load_dwordx4 v[232:235], v[70:71], off offset:480
	v_pk_mul_f32 v[32:33], v[32:33], v[72:73] op_sel_hi:[1,0]
	v_pk_mul_f32 v[34:35], v[34:35], v[72:73] op_sel_hi:[1,0]
	s_waitcnt vmcnt(7)
	v_lshlrev_b32_e32 v74, 16, v236
	v_and_b32_e32 v75, 0xffff0000, v236
	v_lshlrev_b32_e32 v76, 16, v237
	v_and_b32_e32 v77, 0xffff0000, v237
	v_pk_mul_f32 v[32:33], v[32:33], v[204:205]
	v_pk_mul_f32 v[34:35], v[34:35], v[206:207]
	v_pk_mul_f32 v[32:33], v[32:33], v[74:75]
	v_pk_mul_f32 v[34:35], v[34:35], v[76:77]
	v_cvt_pk_bf16_f32 v32, v32, v33
	v_cvt_pk_bf16_f32 v33, v34, v35
	global_store_dwordx2 v[68:69], v[32:33], off offset:128
	v_pk_mul_f32 v[36:37], v[36:37], v[72:73] op_sel_hi:[1,0]
	v_pk_mul_f32 v[38:39], v[38:39], v[72:73] op_sel_hi:[1,0]
	s_waitcnt vmcnt(7)
	v_lshlrev_b32_e32 v74, 16, v238
	v_and_b32_e32 v75, 0xffff0000, v238
	v_lshlrev_b32_e32 v76, 16, v239
	v_and_b32_e32 v77, 0xffff0000, v239
	v_pk_mul_f32 v[36:37], v[36:37], v[208:209]
	v_pk_mul_f32 v[38:39], v[38:39], v[210:211]
	v_pk_mul_f32 v[36:37], v[36:37], v[74:75]
	v_pk_mul_f32 v[38:39], v[38:39], v[76:77]
	v_cvt_pk_bf16_f32 v36, v36, v37
	v_cvt_pk_bf16_f32 v37, v38, v39
	global_store_dwordx2 v[68:69], v[36:37], off offset:144
	v_pk_mul_f32 v[40:41], v[40:41], v[72:73] op_sel_hi:[1,0]
	v_pk_mul_f32 v[42:43], v[42:43], v[72:73] op_sel_hi:[1,0]
	s_waitcnt vmcnt(7)
	v_lshlrev_b32_e32 v74, 16, v240
	v_and_b32_e32 v75, 0xffff0000, v240
	v_lshlrev_b32_e32 v76, 16, v241
	v_and_b32_e32 v77, 0xffff0000, v241
	v_pk_mul_f32 v[40:41], v[40:41], v[212:213]
	v_pk_mul_f32 v[42:43], v[42:43], v[214:215]
	v_pk_mul_f32 v[40:41], v[40:41], v[74:75]
	v_pk_mul_f32 v[42:43], v[42:43], v[76:77]
	v_cvt_pk_bf16_f32 v40, v40, v41
	v_cvt_pk_bf16_f32 v41, v42, v43
	global_store_dwordx2 v[68:69], v[40:41], off offset:160
	v_pk_mul_f32 v[44:45], v[44:45], v[72:73] op_sel_hi:[1,0]
	v_pk_mul_f32 v[46:47], v[46:47], v[72:73] op_sel_hi:[1,0]
	s_waitcnt vmcnt(7)
	v_lshlrev_b32_e32 v74, 16, v242
	v_and_b32_e32 v75, 0xffff0000, v242
	v_lshlrev_b32_e32 v76, 16, v243
	v_and_b32_e32 v77, 0xffff0000, v243
	v_pk_mul_f32 v[44:45], v[44:45], v[216:217]
	v_pk_mul_f32 v[46:47], v[46:47], v[218:219]
	v_pk_mul_f32 v[44:45], v[44:45], v[74:75]
	v_pk_mul_f32 v[46:47], v[46:47], v[76:77]
	v_cvt_pk_bf16_f32 v44, v44, v45
	v_cvt_pk_bf16_f32 v45, v46, v47
	global_store_dwordx2 v[68:69], v[44:45], off offset:176
	v_pk_mul_f32 v[0:1], v[0:1], v[72:73] op_sel_hi:[1,0]
	v_pk_mul_f32 v[2:3], v[2:3], v[72:73] op_sel_hi:[1,0]
	s_waitcnt vmcnt(7)
	v_lshlrev_b32_e32 v74, 16, v244
	v_and_b32_e32 v75, 0xffff0000, v244
	v_lshlrev_b32_e32 v76, 16, v245
	v_and_b32_e32 v77, 0xffff0000, v245
	v_pk_mul_f32 v[0:1], v[0:1], v[220:221]
	v_pk_mul_f32 v[2:3], v[2:3], v[222:223]
	v_pk_mul_f32 v[0:1], v[0:1], v[74:75]
	v_pk_mul_f32 v[2:3], v[2:3], v[76:77]
	v_cvt_pk_bf16_f32 v0, v0, v1
	v_cvt_pk_bf16_f32 v1, v2, v3
	global_store_dwordx2 v[68:69], v[0:1], off offset:192
	v_pk_mul_f32 v[4:5], v[4:5], v[72:73] op_sel_hi:[1,0]
	v_pk_mul_f32 v[6:7], v[6:7], v[72:73] op_sel_hi:[1,0]
	s_waitcnt vmcnt(7)
	v_lshlrev_b32_e32 v74, 16, v246
	v_and_b32_e32 v75, 0xffff0000, v246
	v_lshlrev_b32_e32 v76, 16, v247
	v_and_b32_e32 v77, 0xffff0000, v247
	v_pk_mul_f32 v[4:5], v[4:5], v[224:225]
	v_pk_mul_f32 v[6:7], v[6:7], v[226:227]
	v_pk_mul_f32 v[4:5], v[4:5], v[74:75]
	v_pk_mul_f32 v[6:7], v[6:7], v[76:77]
	v_cvt_pk_bf16_f32 v4, v4, v5
	v_cvt_pk_bf16_f32 v5, v6, v7
	global_store_dwordx2 v[68:69], v[4:5], off offset:208
	v_pk_mul_f32 v[8:9], v[8:9], v[72:73] op_sel_hi:[1,0]
	v_pk_mul_f32 v[10:11], v[10:11], v[72:73] op_sel_hi:[1,0]
	s_waitcnt vmcnt(7)
	v_lshlrev_b32_e32 v74, 16, v248
	v_and_b32_e32 v75, 0xffff0000, v248
	v_lshlrev_b32_e32 v76, 16, v249
	v_and_b32_e32 v77, 0xffff0000, v249
	v_pk_mul_f32 v[8:9], v[8:9], v[228:229]
	v_pk_mul_f32 v[10:11], v[10:11], v[230:231]
	v_pk_mul_f32 v[8:9], v[8:9], v[74:75]
	v_pk_mul_f32 v[10:11], v[10:11], v[76:77]
	v_cvt_pk_bf16_f32 v8, v8, v9
	v_cvt_pk_bf16_f32 v9, v10, v11
	global_store_dwordx2 v[68:69], v[8:9], off offset:224
	v_pk_mul_f32 v[12:13], v[12:13], v[72:73] op_sel_hi:[1,0]
	v_pk_mul_f32 v[14:15], v[14:15], v[72:73] op_sel_hi:[1,0]
	s_waitcnt vmcnt(7)
	v_lshlrev_b32_e32 v74, 16, v250
	v_and_b32_e32 v75, 0xffff0000, v250
	v_lshlrev_b32_e32 v76, 16, v251
	v_and_b32_e32 v77, 0xffff0000, v251
	v_pk_mul_f32 v[12:13], v[12:13], v[232:233]
	v_pk_mul_f32 v[14:15], v[14:15], v[234:235]
	v_pk_mul_f32 v[12:13], v[12:13], v[74:75]
	v_pk_mul_f32 v[14:15], v[14:15], v[76:77]
	v_cvt_pk_bf16_f32 v12, v12, v13
	v_cvt_pk_bf16_f32 v13, v14, v15
	global_store_dwordx2 v[68:69], v[12:13], off offset:240
	s_branch .LBB0_1008

; #define LAS __attribute__((address_space(3)))
; __global__ void __launch_bounds__(512, 2) fwd_megakernel(Params p) {
;     extern __shared__ __attribute__((aligned(16))) unsigned char lds_raw[];
;     LAS unsigned char* lds = (LAS unsigned char*)lds_raw;
;     if (threadIdx.x < 4) ((volatile LAS unsigned*)(lds + LDS_BAR))[threadIdx.x] = 0u;
;     __syncthreads();
;     const XcdBarrier bar = xcd_barrier_post((unsigned*)(p.ws + OFF_BAR), (volatile LAS unsigned*)(lds + LDS_BAR));
;     if (p.ws == nullptr) cg::this_grid().sync();
;     p0_prep(p, lds);
;     xcd_barrier(bar);
;     gemm_phase<1>(p, lds, 0);
;     { const int nfull = (66 * 17 + 4 + 24) % (int)gridDim.x, nslack = (int)gridDim.x - nfull;
;       if (nslack >= 32) { if ((int)blockIdx.x >= nfull) p0_caches(p, lds, (int)blockIdx.x - nfull, nslack); } else p0_caches(p, lds, (int)blockIdx.x, (int)gridDim.x); }
;     xcd_barrier(bar);
;     p2_mixers(p, lds);
;     xcd_barrier(bar);
;     p3_scan(p);
;     xcd_barrier(bar);
;     p4_gla_out(p, lds);
;     xcd_barrier(bar);
;     gemm_phase<5>(p, lds, 0);
;     xcd_barrier(bar);
;     gemm_phase<6>(p, lds, 0);
; }
	.amdhsa_kernel _Z14fwd_megakernel6Params
		.amdhsa_group_segment_fixed_size 0
		.amdhsa_private_segment_fixed_size 0
		.amdhsa_kernarg_size 464
		.amdhsa_user_sgpr_count 2
		.amdhsa_user_sgpr_dispatch_ptr 0
		.amdhsa_user_sgpr_queue_ptr 0
		.amdhsa_user_sgpr_kernarg_segment_ptr 1
		.amdhsa_user_sgpr_dispatch_id 0
		.amdhsa_user_sgpr_kernarg_preload_length 0
		.amdhsa_user_sgpr_kernarg_preload_offset 0
		.amdhsa_user_sgpr_private_segment_size 0
		.amdhsa_uses_dynamic_stack 0
		.amdhsa_enable_private_segment 0
		.amdhsa_system_sgpr_workgroup_id_x 1
		.amdhsa_system_sgpr_workgroup_id_y 0
		.amdhsa_system_sgpr_workgroup_id_z 0
		.amdhsa_system_sgpr_workgroup_info 0
		.amdhsa_system_vgpr_workitem_id 2
		.amdhsa_next_free_vgpr 256
		.amdhsa_next_free_sgpr 102
		.amdhsa_accum_offset 256
		.amdhsa_reserve_vcc 1
		.amdhsa_float_round_mode_32 0
		.amdhsa_float_round_mode_16_64 0
		.amdhsa_float_denorm_mode_32 3
		.amdhsa_float_denorm_mode_16_64 3
		.amdhsa_dx10_clamp 1
		.amdhsa_ieee_mode 1
		.amdhsa_fp16_overflow 0
		.amdhsa_tg_split 0
		.amdhsa_exception_fp_ieee_invalid_op 0
		.amdhsa_exception_fp_denorm_src 0
		.amdhsa_exception_fp_ieee_div_zero 0
		.amdhsa_exception_fp_ieee_overflow 0
		.amdhsa_exception_fp_ieee_underflow 0
		.amdhsa_exception_fp_ieee_inexact 0
		.amdhsa_exception_int_div_zero 0
	.end_amdhsa_kernel

; #define LAS __attribute__((address_space(3)))
; __global__ void __launch_bounds__(512, 2) fwd_megakernel(Params p) {
;     extern __shared__ __attribute__((aligned(16))) unsigned char lds_raw[];
;     LAS unsigned char* lds = (LAS unsigned char*)lds_raw;
amdhsa.kernels:
  - .agpr_count:     0
    .args:
      - .offset:         0
        .size:           208
        .value_kind:     by_value
      - .offset:         208
        .size:           4
        .value_kind:     hidden_block_count_x
      - .offset:         212
        .size:           4
        .value_kind:     hidden_block_count_y
      - .offset:         216
        .size:           4
        .value_kind:     hidden_block_count_z
      - .offset:         220
        .size:           2
        .value_kind:     hidden_group_size_x
      - .offset:         222
        .size:           2
        .value_kind:     hidden_group_size_y
      - .offset:         224
        .size:           2
        .value_kind:     hidden_group_size_z
      - .offset:         226
        .size:           2
        .value_kind:     hidden_remainder_x
      - .offset:         228
        .size:           2
        .value_kind:     hidden_remainder_y
      - .offset:         230
        .size:           2
        .value_kind:     hidden_remainder_z
      - .offset:         248
        .size:           8
        .value_kind:     hidden_global_offset_x
      - .offset:         256
        .size:           8
        .value_kind:     hidden_global_offset_y
      - .offset:         264
        .size:           8
        .value_kind:     hidden_global_offset_z
      - .offset:         272
        .size:           2
        .value_kind:     hidden_grid_dims
      - .offset:         296
        .size:           8
        .value_kind:     hidden_multigrid_sync_arg
      - .offset:         328
        .size:           4
        .value_kind:     hidden_dynamic_lds_size
    .group_segment_fixed_size: 0
    .kernarg_segment_align: 8
    .kernarg_segment_size: 464
    .language:       OpenCL C
    .language_version:
      - 2
      - 0
    .max_flat_workgroup_size: 512
    .name:           _Z14fwd_megakernel6Params
    .private_segment_fixed_size: 0
    .sgpr_count:     108
    .sgpr_spill_count: 9
    .symbol:         _Z14fwd_megakernel6Params.kd
    .uniform_work_group_size: 1
    .uses_dynamic_stack: false
    .vgpr_count:     256
    .vgpr_spill_count: 0
    .wavefront_size: 64
